# in-proj: column tile 14 (beta/g, 8 real columns) runs a copy of the K loop without the MFMAs of the 16 accumulators its epilogue never reads
# baseline (speedup 1.0000x reference)
.LBB0_252:
	s_add_u32 s12, s6, 0xec00000
	s_addc_u32 s13, s7, 0
	s_add_u32 s14, s6, 0x1ac00000
	s_addc_u32 s15, s7, 0
	s_add_u32 s18, s6, 0x1ec00000
	s_addc_u32 s19, s7, 0
	s_add_u32 s20, s6, 0xea00000
	s_addc_u32 s21, s7, 0
	s_lshl_b32 s68, s84, 2
	s_lshl_b64 s[24:25], s[68:69], 2
	s_waitcnt lgkmcnt(0)
	s_add_u32 s22, s22, s24
	s_addc_u32 s23, s23, s25
	s_add_u32 s24, s4, s24
	s_addc_u32 s25, s5, s25
	s_and_b32 s29, s28, 3
	s_add_i32 m0, s55, 0x18000
	v_lshl_add_u64 v[6:7], v[6:7], 0, s[76:77]
	s_lshl_b32 s30, s27, 13
	s_lshl_b32 s31, s29, 12
	s_waitcnt vmcnt(2)
	s_barrier
	global_load_lds_dwordx4 v[6:7], off
	v_lshl_add_u64 v[4:5], v[4:5], 0, s[76:77]
	s_add_i32 m0, s55, 0x1a000
	s_add_i32 s68, s55, 0x8000
	s_add_i32 s83, s55, 0xa000
	global_load_lds_dwordx4 v[4:5], off
	v_lshl_add_u64 v[0:1], v[0:1], 0, s[76:77]
	s_mov_b32 m0, s68
	s_add_u32 s4, s8, 0x40080
	global_load_lds_dwordx4 v[0:1], off
	v_lshl_add_u64 v[0:1], v[2:3], 0, s[76:77]
	s_mov_b32 m0, s83
	s_addc_u32 s5, s9, 0
	global_load_lds_dwordx4 v[0:1], off
	s_add_i32 m0, s55, 0x1c000
	v_lshl_add_u64 v[0:1], s[4:5], 0, v[192:193]
	global_load_lds_dwordx4 v[0:1], off
	v_lshl_add_u64 v[0:1], s[4:5], 0, v[152:153]
	s_add_i32 m0, s55, 0x1e000
	v_and_b32_e32 v2, 15, v8
	global_load_lds_dwordx4 v[0:1], off
	v_lshrrev_b32_e32 v1, 4, v8
	v_bfe_u32 v0, v8, 4, 2
	v_bitop3_b32 v1, s28, v1, 3 bitop3:0xa8
	v_lshlrev_b32_e32 v3, 3, v0
	v_lshlrev_b32_e32 v0, 4, v0
	v_cmp_eq_u32_e64 s[4:5], 0, v1
	v_mov_b32_e32 v1, v193
	v_lshl_or_b32 v181, s27, 6, v2
	v_lshl_or_b32 v2, v2, 6, v0
	v_lshl_add_u64 v[0:1], s[6:7], 0, v[0:1]
	s_mov_b64 s[6:7], 0x3cc00000
	v_lshl_add_u64 v[158:159], v[0:1], 0, s[6:7]
	v_lshlrev_b32_e32 v0, 14, v9
	v_and_b32_e32 v0, 0xffff8000, v0
	v_lshl_add_u32 v0, v10, 11, v0
	v_and_b32_e32 v1, 1, v9
	v_lshl_or_b32 v0, v1, 6, v0
	v_lshl_add_u32 v160, v11, 1, v0
	v_lshlrev_b32_e32 v0, 14, v13
	v_lshlrev_b32_e32 v4, 2, v8
	v_and_b32_e32 v0, 0xffff8000, v0
	v_and_b32_e32 v4, 32, v4
	s_waitcnt vmcnt(6)
	v_lshl_add_u32 v0, v12, 11, v0
	v_and_b32_e32 v1, 1, v13
	v_bitop3_b32 v5, v2, s30, v4 bitop3:0xde
	s_cmpk_lt_u32 s26, 0x100
	v_lshl_or_b32 v0, v1, 6, v0
	v_readlane_b32 s6, v255, 34
	v_bitop3_b32 v183, v2, s31, v4 bitop3:0xde
	s_cselect_b64 s[26:27], -1, 0
	s_mov_b32 s85, 0
	v_lshl_or_b32 v186, s29, 5, v3
	v_mov_b32_e32 v161, v193
	v_lshl_add_u32 v162, v14, 1, v0
	v_mov_b32_e32 v163, v193
	v_add_u32_e32 v187, 0, v5
	v_readlane_b32 s86, v255, 18
	s_mov_b32 s46, s6
	s_barrier
	v_readlane_b32 s7, v255, 35
	s_branch .LBB0_255
.Lz255:
	s_add_u32 s88, s8, 0x100
	s_addc_u32 s89, s9, 0
	s_add_u32 s8, s38, 0x40080
	s_addc_u32 s9, s39, 0
	s_mov_b32 s90, -2
	s_add_u32 s38, s8, 0xfffc0080
	s_addc_u32 s39, s9, -1
	s_add_i32 s91, 0, 0x10000
	s_cmp_eq_u32 s90, 12
	s_cselect_b32 s57, s31, s39
	s_cselect_b32 s56, s47, s38
	s_cselect_b32 s39, s29, s89
	s_cselect_b32 s38, s87, s88
	s_add_i32 s94, 0, 0x14000
	v_add_u32_e32 v140, s91, v183
	v_add_u32_e32 v168, s94, v183
	ds_read_b128 v[128:131], v140
	ds_read_b128 v[132:135], v140 offset:1024
	ds_read_b128 v[136:139], v140 offset:2048
	ds_read_b128 v[140:143], v140 offset:3072
	ds_read_b128 v[144:147], v168
	ds_read_b128 v[148:151], v168 offset:1024
	ds_read_b128 v[164:167], v168 offset:2048
	ds_read_b128 v[168:171], v168 offset:3072
	v_lshl_add_u64 v[184:185], s[8:9], 0, v[162:163]
	s_add_i32 m0, s55, 0xc000
	ds_read_b128 v[172:175], v187
	ds_read_b128 v[176:179], v187 offset:1024
	ds_read_b128 v[188:191], v187 offset:2048
	ds_read_b128 v[202:205], v187 offset:3072
	ds_read_b128 v[206:209], v187 offset:4096
	ds_read_b128 v[210:213], v187 offset:5120
	ds_read_b128 v[214:217], v187 offset:6144
	ds_read_b128 v[218:221], v187 offset:7168
	global_load_lds_dwordx4 v[184:185], off
	v_lshl_add_u64 v[184:185], s[8:9], 0, v[160:161]
	s_add_i32 m0, s55, 0xe000
	s_nop 0
	global_load_lds_dwordx4 v[184:185], off
	s_add_i32 s85, s85, 1
	s_mul_i32 s6, s85, s43
	s_mul_hi_u32 s7, s85, s42
	s_add_i32 s7, s7, s6
	s_mul_i32 s6, s85, s42
	s_add_u32 s34, s6, s2
	s_addc_u32 s35, s7, s41
	v_mov_b64_e32 v[0:1], 0xf00
	v_cmp_lt_i64_e64 s[6:7], s[34:35], v[0:1]
	v_mov_b64_e32 v[0:1], 0xeff
	v_cmp_gt_i64_e32 vcc, s[34:35], v[0:1]
	s_cbranch_vccnz .Lz257
	s_ashr_i32 s28, s34, 31
	s_lshr_b32 s28, s28, 29
	s_add_i32 s28, s34, s28
	s_ashr_i32 s29, s28, 3
	s_and_b32 s28, s28, -8
	s_sub_i32 s28, s34, s28
	s_cmp_lt_i32 s28, 0
	s_movk_i32 s30, 0x1e1
	s_cselect_b32 s30, s30, 0x1e0
	s_mul_i32 s28, s28, s30
	s_add_i32 s28, s28, s29
	s_mul_hi_i32 s29, s28, 0x88888889
	s_add_i32 s29, s29, s28
	s_lshr_b32 s30, s29, 31
	s_ashr_i32 s29, s29, 6
	s_add_i32 s29, s29, s30
	s_lshl_b32 s30, s29, 3
	s_sub_i32 s31, 0x100, s30
	s_min_i32 s31, s31, 8
	s_abs_i32 s34, s31
	v_cvt_f32_u32_e32 v0, s34
	s_sub_i32 s36, 0, s34
	s_mulk_i32 s29, 0x78
	s_sub_i32 s29, s28, s29
	v_rcp_iflag_f32_e32 v0, v0
	s_abs_i32 s28, s29
	s_xor_b32 s35, s29, s31
	s_ashr_i32 s35, s35, 31
	v_mul_f32_e32 v0, 0x4f7ffffe, v0
	v_cvt_u32_f32_e32 v0, v0
	s_nop 0
	v_readfirstlane_b32 s37, v0
	s_mul_i32 s36, s36, s37
	s_mul_hi_u32 s36, s37, s36
	s_add_i32 s37, s37, s36
	s_mul_hi_u32 s36, s28, s37
	s_mul_i32 s37, s36, s34
	s_sub_i32 s28, s28, s37
	s_add_i32 s47, s36, 1
	s_sub_i32 s37, s28, s34
	s_cmp_ge_u32 s28, s34
	s_cselect_b32 s36, s47, s36
	s_cselect_b32 s28, s37, s28
	s_add_i32 s37, s36, 1
	s_cmp_ge_u32 s28, s34
	s_cselect_b32 s28, s37, s36
	s_xor_b32 s28, s28, s35
	s_sub_i32 s28, s28, s35
	s_mul_i32 s31, s28, s31
	s_sub_i32 s29, s29, s31
	s_add_i32 s30, s30, s29
.Lz257:
	s_ashr_i32 s31, s30, 31
	s_lshl_b64 s[34:35], s[30:31], 19
	s_add_u32 s34, s48, s34
	s_addc_u32 s35, s49, s35
	s_and_b64 s[36:37], s[6:7], exec
	s_cselect_b32 s31, s35, s57
	s_cselect_b32 s47, s34, s56
	s_ashr_i32 s29, s28, 31
	s_lshl_b64 s[36:37], s[28:29], 19
	s_add_u32 s36, s50, s36
	s_addc_u32 s37, s51, s37
	s_and_b64 s[100:101], s[6:7], exec
	s_cselect_b32 s29, s37, s89
	s_cselect_b32 s87, s36, s88
	s_waitcnt vmcnt(8)
	s_waitcnt lgkmcnt(0)
	s_barrier
	s_setprio 1
	s_waitcnt lgkmcnt(0)
	v_mfma_f32_16x16x32_bf16 v[124:127], v[128:131], v[172:175], 0
	v_mfma_f32_16x16x32_bf16 v[120:123], v[136:139], v[172:175], 0
	v_mfma_f32_16x16x32_bf16 v[112:115], v[128:131], v[188:191], 0
	v_mfma_f32_16x16x32_bf16 v[104:107], v[136:139], v[188:191], 0
	v_mfma_f32_16x16x32_bf16 v[96:99], v[128:131], v[206:209], 0
	v_mfma_f32_16x16x32_bf16 v[88:91], v[136:139], v[206:209], 0
	v_mfma_f32_16x16x32_bf16 v[80:83], v[128:131], v[214:217], 0
	v_mfma_f32_16x16x32_bf16 v[72:75], v[136:139], v[214:217], 0
	v_mfma_f32_16x16x32_bf16 v[124:127], v[132:135], v[176:179], v[124:127]
	v_mfma_f32_16x16x32_bf16 v[120:123], v[140:143], v[176:179], v[120:123]
	v_mfma_f32_16x16x32_bf16 v[112:115], v[132:135], v[202:205], v[112:115]
	v_mfma_f32_16x16x32_bf16 v[104:107], v[140:143], v[202:205], v[104:107]
	v_mfma_f32_16x16x32_bf16 v[96:99], v[132:135], v[210:213], v[96:99]
	v_mfma_f32_16x16x32_bf16 v[88:91], v[140:143], v[210:213], v[88:91]
	v_mfma_f32_16x16x32_bf16 v[80:83], v[132:135], v[218:221], v[80:83]
	v_mfma_f32_16x16x32_bf16 v[72:75], v[140:143], v[218:221], v[72:75]
	s_setprio 0
	s_setprio 1
	s_setprio 0
	s_barrier
	s_add_i32 s91, s91, s54
	v_lshl_add_u64 v[184:185], s[38:39], 0, v[192:193]
	s_mov_b32 m0, s91
	ds_read_b128 v[172:175], v187 offset:16384
	ds_read_b128 v[176:179], v187 offset:17408
	ds_read_b128 v[188:191], v187 offset:18432
	ds_read_b128 v[202:205], v187 offset:19456
	ds_read_b128 v[206:209], v187 offset:20480
	ds_read_b128 v[210:213], v187 offset:21504
	ds_read_b128 v[214:217], v187 offset:22528
	ds_read_b128 v[218:221], v187 offset:23552
	global_load_lds_dwordx4 v[184:185], off
	s_add_i32 m0, s91, 0x2000
	s_add_u32 s92, s38, 0x40000
	v_lshl_add_u64 v[222:223], s[38:39], 0, v[152:153]
	s_addc_u32 s93, s39, 0
	s_add_i32 s91, s94, s54
	global_load_lds_dwordx4 v[222:223], off
	v_lshl_add_u64 v[224:225], s[92:93], 0, v[192:193]
	s_mov_b32 m0, s91
	v_lshl_add_u64 v[226:227], s[56:57], 0, v[154:155]
	global_load_lds_dwordx4 v[224:225], off
	v_lshl_add_u64 v[224:225], s[92:93], 0, v[152:153]
	s_add_i32 m0, s91, 0x2000
	s_nop 0
	global_load_lds_dwordx4 v[224:225], off
	v_lshl_add_u64 v[224:225], s[56:57], 0, v[156:157]
	s_mov_b32 m0, s55
	s_nop 0
	global_load_lds_dwordx4 v[224:225], off
	s_mov_b32 m0, s60
	s_nop 0
	global_load_lds_dwordx4 v[226:227], off
	s_waitcnt vmcnt(8)
	s_waitcnt lgkmcnt(0)
	s_barrier
	s_setprio 1
	s_waitcnt lgkmcnt(0)
	v_mfma_f32_16x16x32_bf16 v[60:63], v[128:131], v[172:175], 0
	v_mfma_f32_16x16x32_bf16 v[56:59], v[136:139], v[172:175], 0
	v_mfma_f32_16x16x32_bf16 v[48:51], v[128:131], v[188:191], 0
	v_mfma_f32_16x16x32_bf16 v[40:43], v[136:139], v[188:191], 0
	v_mfma_f32_16x16x32_bf16 v[32:35], v[128:131], v[206:209], 0
	v_mfma_f32_16x16x32_bf16 v[24:27], v[136:139], v[206:209], 0
	v_mfma_f32_16x16x32_bf16 v[16:19], v[128:131], v[214:217], 0
	v_mfma_f32_16x16x32_bf16 v[8:11], v[136:139], v[214:217], 0
	v_mfma_f32_16x16x32_bf16 v[60:63], v[132:135], v[176:179], v[60:63]
	v_mfma_f32_16x16x32_bf16 v[56:59], v[140:143], v[176:179], v[56:59]
	v_mfma_f32_16x16x32_bf16 v[48:51], v[132:135], v[202:205], v[48:51]
	v_mfma_f32_16x16x32_bf16 v[40:43], v[140:143], v[202:205], v[40:43]
	v_mfma_f32_16x16x32_bf16 v[32:35], v[132:135], v[210:213], v[32:35]
	v_mfma_f32_16x16x32_bf16 v[24:27], v[140:143], v[210:213], v[24:27]
	v_mfma_f32_16x16x32_bf16 v[16:19], v[132:135], v[218:221], v[16:19]
	v_mfma_f32_16x16x32_bf16 v[8:11], v[140:143], v[218:221], v[8:11]
	s_setprio 0
	s_setprio 1
	s_setprio 0
	s_barrier
	s_add_i32 s91, 0, 0x18000
	s_add_i32 s92, 0, 0x1c000
	v_add_u32_e32 v140, s91, v183
	v_add_u32_e32 v168, s92, v183
	ds_read_b128 v[128:131], v140
	ds_read_b128 v[132:135], v140 offset:1024
	ds_read_b128 v[136:139], v140 offset:2048
	ds_read_b128 v[140:143], v140 offset:3072
	ds_read_b128 v[144:147], v168
	ds_read_b128 v[148:151], v168 offset:1024
	ds_read_b128 v[164:167], v168 offset:2048
	ds_read_b128 v[168:171], v168 offset:3072
	s_add_u32 s56, s56, 0x40000
	s_addc_u32 s57, s57, 0
	s_mov_b32 m0, s61
	v_lshl_add_u64 v[228:229], s[56:57], 0, v[156:157]
	ds_read_b128 v[172:175], v187 offset:32768
	ds_read_b128 v[176:179], v187 offset:33792
	ds_read_b128 v[188:191], v187 offset:34816
	ds_read_b128 v[202:205], v187 offset:35840
	ds_read_b128 v[206:209], v187 offset:36864
	ds_read_b128 v[210:213], v187 offset:37888
	ds_read_b128 v[214:217], v187 offset:38912
	ds_read_b128 v[218:221], v187 offset:39936
	global_load_lds_dwordx4 v[228:229], off
	v_lshl_add_u64 v[228:229], s[56:57], 0, v[154:155]
	s_mov_b32 m0, s82
	s_nop 0
	global_load_lds_dwordx4 v[228:229], off
	s_waitcnt vmcnt(8)
	s_waitcnt lgkmcnt(0)
	s_barrier
	s_setprio 1
	s_waitcnt lgkmcnt(0)
	v_mfma_f32_16x16x32_bf16 v[124:127], v[128:131], v[172:175], v[124:127]
	v_mfma_f32_16x16x32_bf16 v[120:123], v[136:139], v[172:175], v[120:123]
	v_mfma_f32_16x16x32_bf16 v[112:115], v[128:131], v[188:191], v[112:115]
	v_mfma_f32_16x16x32_bf16 v[104:107], v[136:139], v[188:191], v[104:107]
	v_mfma_f32_16x16x32_bf16 v[96:99], v[128:131], v[206:209], v[96:99]
	v_mfma_f32_16x16x32_bf16 v[88:91], v[136:139], v[206:209], v[88:91]
	v_mfma_f32_16x16x32_bf16 v[80:83], v[128:131], v[214:217], v[80:83]
	v_mfma_f32_16x16x32_bf16 v[72:75], v[136:139], v[214:217], v[72:75]
	v_mfma_f32_16x16x32_bf16 v[124:127], v[132:135], v[176:179], v[124:127]
	v_mfma_f32_16x16x32_bf16 v[120:123], v[140:143], v[176:179], v[120:123]
	v_mfma_f32_16x16x32_bf16 v[112:115], v[132:135], v[202:205], v[112:115]
	v_mfma_f32_16x16x32_bf16 v[104:107], v[140:143], v[202:205], v[104:107]
	v_mfma_f32_16x16x32_bf16 v[96:99], v[132:135], v[210:213], v[96:99]
	v_mfma_f32_16x16x32_bf16 v[88:91], v[140:143], v[210:213], v[88:91]
	v_mfma_f32_16x16x32_bf16 v[80:83], v[132:135], v[218:221], v[80:83]
	v_mfma_f32_16x16x32_bf16 v[72:75], v[140:143], v[218:221], v[72:75]
	s_setprio 0
	s_setprio 1
	s_setprio 0
	s_barrier
	s_add_i32 s56, s91, s54
	v_lshl_add_u64 v[184:185], v[184:185], 0, s[76:77]
	s_mov_b32 m0, s56
	ds_read_b128 v[172:175], v187 offset:49152
	ds_read_b128 v[176:179], v187 offset:50176
	ds_read_b128 v[188:191], v187 offset:51200
	ds_read_b128 v[202:205], v187 offset:52224
	ds_read_b128 v[206:209], v187 offset:53248
	ds_read_b128 v[210:213], v187 offset:54272
	ds_read_b128 v[214:217], v187 offset:55296
	ds_read_b128 v[218:221], v187 offset:56320
	global_load_lds_dwordx4 v[184:185], off
	s_add_i32 m0, s56, 0x2000
	s_add_u32 s38, s38, 0x40080
	v_lshl_add_u64 v[184:185], v[222:223], 0, s[76:77]
	s_addc_u32 s39, s39, 0
	s_add_i32 s56, s92, s54
	global_load_lds_dwordx4 v[184:185], off
	v_lshl_add_u64 v[184:185], s[38:39], 0, v[192:193]
	s_mov_b32 m0, s56
	s_nop 0
	global_load_lds_dwordx4 v[184:185], off
	v_lshl_add_u64 v[184:185], s[38:39], 0, v[152:153]
	s_add_i32 m0, s56, 0x2000
	s_nop 0
	global_load_lds_dwordx4 v[184:185], off
	v_lshl_add_u64 v[184:185], v[224:225], 0, s[76:77]
	s_mov_b32 m0, s68
	s_nop 0
	global_load_lds_dwordx4 v[184:185], off
	v_lshl_add_u64 v[184:185], v[226:227], 0, s[76:77]
	s_mov_b32 m0, s83
	s_nop 0
	global_load_lds_dwordx4 v[184:185], off
	s_waitcnt vmcnt(8)
	s_waitcnt lgkmcnt(0)
	s_barrier
	s_setprio 1
	s_waitcnt lgkmcnt(0)
	v_mfma_f32_16x16x32_bf16 v[60:63], v[128:131], v[172:175], v[60:63]
	v_mfma_f32_16x16x32_bf16 v[56:59], v[136:139], v[172:175], v[56:59]
	v_mfma_f32_16x16x32_bf16 v[48:51], v[128:131], v[188:191], v[48:51]
	v_mfma_f32_16x16x32_bf16 v[40:43], v[136:139], v[188:191], v[40:43]
	v_mfma_f32_16x16x32_bf16 v[32:35], v[128:131], v[206:209], v[32:35]
	v_mfma_f32_16x16x32_bf16 v[24:27], v[136:139], v[206:209], v[24:27]
	v_mfma_f32_16x16x32_bf16 v[16:19], v[128:131], v[214:217], v[16:19]
	v_mfma_f32_16x16x32_bf16 v[8:11], v[136:139], v[214:217], v[8:11]
	v_mfma_f32_16x16x32_bf16 v[60:63], v[132:135], v[176:179], v[60:63]
	v_mfma_f32_16x16x32_bf16 v[56:59], v[140:143], v[176:179], v[56:59]
	v_mfma_f32_16x16x32_bf16 v[48:51], v[132:135], v[202:205], v[48:51]
	v_mfma_f32_16x16x32_bf16 v[40:43], v[140:143], v[202:205], v[40:43]
	v_mfma_f32_16x16x32_bf16 v[32:35], v[132:135], v[210:213], v[32:35]
	v_mfma_f32_16x16x32_bf16 v[24:27], v[140:143], v[210:213], v[24:27]
	v_mfma_f32_16x16x32_bf16 v[16:19], v[132:135], v[218:221], v[16:19]
	v_mfma_f32_16x16x32_bf16 v[8:11], v[140:143], v[218:221], v[8:11]
	s_setprio 0
	s_setprio 1
	s_setprio 0
	s_barrier
	s_add_i32 s90, s90, 2
	s_add_u32 s88, s88, 0x100
	s_addc_u32 s89, s89, 0
	s_add_u32 s8, s8, 0x100
	s_addc_u32 s9, s9, 0
	s_cmp_gt_u32 s90, 13
.Lz258:
	s_add_u32 s38, s8, 0xfffc0080
	s_addc_u32 s39, s9, -1
	s_add_i32 s91, 0, 0x10000
	s_cmp_eq_u32 s90, 12
	s_cselect_b32 s57, s31, s39
	s_cselect_b32 s56, s47, s38
	s_cselect_b32 s39, s29, s89
	s_cselect_b32 s38, s87, s88
	s_add_i32 s94, 0, 0x14000
	v_add_u32_e32 v140, s91, v183
	v_add_u32_e32 v168, s94, v183
	ds_read_b128 v[128:131], v140
	ds_read_b128 v[132:135], v140 offset:1024
	ds_read_b128 v[136:139], v140 offset:2048
	ds_read_b128 v[140:143], v140 offset:3072
	ds_read_b128 v[144:147], v168
	ds_read_b128 v[148:151], v168 offset:1024
	ds_read_b128 v[164:167], v168 offset:2048
	ds_read_b128 v[168:171], v168 offset:3072
	v_lshl_add_u64 v[184:185], s[8:9], 0, v[162:163]
	s_add_i32 m0, s55, 0xc000
	ds_read_b128 v[172:175], v187
	ds_read_b128 v[176:179], v187 offset:1024
	ds_read_b128 v[188:191], v187 offset:2048
	ds_read_b128 v[202:205], v187 offset:3072
	ds_read_b128 v[206:209], v187 offset:4096
	ds_read_b128 v[210:213], v187 offset:5120
	ds_read_b128 v[214:217], v187 offset:6144
	ds_read_b128 v[218:221], v187 offset:7168
	global_load_lds_dwordx4 v[184:185], off
	v_lshl_add_u64 v[184:185], s[8:9], 0, v[160:161]
	s_add_i32 m0, s55, 0xe000
	s_nop 0
	global_load_lds_dwordx4 v[184:185], off
	s_waitcnt vmcnt(8)
	s_waitcnt lgkmcnt(0)
	s_barrier
	s_setprio 1
	s_waitcnt lgkmcnt(0)
	v_mfma_f32_16x16x32_bf16 v[124:127], v[128:131], v[172:175], v[124:127]
	v_mfma_f32_16x16x32_bf16 v[120:123], v[136:139], v[172:175], v[120:123]
	v_mfma_f32_16x16x32_bf16 v[112:115], v[128:131], v[188:191], v[112:115]
	v_mfma_f32_16x16x32_bf16 v[104:107], v[136:139], v[188:191], v[104:107]
	v_mfma_f32_16x16x32_bf16 v[96:99], v[128:131], v[206:209], v[96:99]
	v_mfma_f32_16x16x32_bf16 v[88:91], v[136:139], v[206:209], v[88:91]
	v_mfma_f32_16x16x32_bf16 v[80:83], v[128:131], v[214:217], v[80:83]
	v_mfma_f32_16x16x32_bf16 v[72:75], v[136:139], v[214:217], v[72:75]
	v_mfma_f32_16x16x32_bf16 v[124:127], v[132:135], v[176:179], v[124:127]
	v_mfma_f32_16x16x32_bf16 v[120:123], v[140:143], v[176:179], v[120:123]
	v_mfma_f32_16x16x32_bf16 v[112:115], v[132:135], v[202:205], v[112:115]
	v_mfma_f32_16x16x32_bf16 v[104:107], v[140:143], v[202:205], v[104:107]
	v_mfma_f32_16x16x32_bf16 v[96:99], v[132:135], v[210:213], v[96:99]
	v_mfma_f32_16x16x32_bf16 v[88:91], v[140:143], v[210:213], v[88:91]
	v_mfma_f32_16x16x32_bf16 v[80:83], v[132:135], v[218:221], v[80:83]
	v_mfma_f32_16x16x32_bf16 v[72:75], v[140:143], v[218:221], v[72:75]
	s_setprio 0
	s_setprio 1
	s_setprio 0
	s_barrier
	s_add_i32 s91, s91, s54
	v_lshl_add_u64 v[184:185], s[38:39], 0, v[192:193]
	s_mov_b32 m0, s91
	ds_read_b128 v[172:175], v187 offset:16384
	ds_read_b128 v[176:179], v187 offset:17408
	ds_read_b128 v[188:191], v187 offset:18432
	ds_read_b128 v[202:205], v187 offset:19456
	ds_read_b128 v[206:209], v187 offset:20480
	ds_read_b128 v[210:213], v187 offset:21504
	ds_read_b128 v[214:217], v187 offset:22528
	ds_read_b128 v[218:221], v187 offset:23552
	global_load_lds_dwordx4 v[184:185], off
	s_add_i32 m0, s91, 0x2000
	s_add_u32 s92, s38, 0x40000
	v_lshl_add_u64 v[222:223], s[38:39], 0, v[152:153]
	s_addc_u32 s93, s39, 0
	s_add_i32 s91, s94, s54
	global_load_lds_dwordx4 v[222:223], off
	v_lshl_add_u64 v[224:225], s[92:93], 0, v[192:193]
	s_mov_b32 m0, s91
	v_lshl_add_u64 v[226:227], s[56:57], 0, v[154:155]
	global_load_lds_dwordx4 v[224:225], off
	v_lshl_add_u64 v[224:225], s[92:93], 0, v[152:153]
	s_add_i32 m0, s91, 0x2000
	s_nop 0
	global_load_lds_dwordx4 v[224:225], off
	v_lshl_add_u64 v[224:225], s[56:57], 0, v[156:157]
	s_mov_b32 m0, s55
	s_nop 0
	global_load_lds_dwordx4 v[224:225], off
	s_mov_b32 m0, s60
	s_nop 0
	global_load_lds_dwordx4 v[226:227], off
	s_waitcnt vmcnt(8)
	s_waitcnt lgkmcnt(0)
	s_barrier
	s_setprio 1
	s_waitcnt lgkmcnt(0)
	v_mfma_f32_16x16x32_bf16 v[60:63], v[128:131], v[172:175], v[60:63]
	v_mfma_f32_16x16x32_bf16 v[56:59], v[136:139], v[172:175], v[56:59]
	v_mfma_f32_16x16x32_bf16 v[48:51], v[128:131], v[188:191], v[48:51]
	v_mfma_f32_16x16x32_bf16 v[40:43], v[136:139], v[188:191], v[40:43]
	v_mfma_f32_16x16x32_bf16 v[32:35], v[128:131], v[206:209], v[32:35]
	v_mfma_f32_16x16x32_bf16 v[24:27], v[136:139], v[206:209], v[24:27]
	v_mfma_f32_16x16x32_bf16 v[16:19], v[128:131], v[214:217], v[16:19]
	v_mfma_f32_16x16x32_bf16 v[8:11], v[136:139], v[214:217], v[8:11]
	v_mfma_f32_16x16x32_bf16 v[60:63], v[132:135], v[176:179], v[60:63]
	v_mfma_f32_16x16x32_bf16 v[56:59], v[140:143], v[176:179], v[56:59]
	v_mfma_f32_16x16x32_bf16 v[48:51], v[132:135], v[202:205], v[48:51]
	v_mfma_f32_16x16x32_bf16 v[40:43], v[140:143], v[202:205], v[40:43]
	v_mfma_f32_16x16x32_bf16 v[32:35], v[132:135], v[210:213], v[32:35]
	v_mfma_f32_16x16x32_bf16 v[24:27], v[140:143], v[210:213], v[24:27]
	v_mfma_f32_16x16x32_bf16 v[16:19], v[132:135], v[218:221], v[16:19]
	v_mfma_f32_16x16x32_bf16 v[8:11], v[140:143], v[218:221], v[8:11]
	s_setprio 0
	s_setprio 1
	s_setprio 0
	s_barrier
	s_add_i32 s91, 0, 0x18000
	s_add_i32 s92, 0, 0x1c000
	v_add_u32_e32 v140, s91, v183
	v_add_u32_e32 v168, s92, v183
	ds_read_b128 v[128:131], v140
	ds_read_b128 v[132:135], v140 offset:1024
	ds_read_b128 v[136:139], v140 offset:2048
	ds_read_b128 v[140:143], v140 offset:3072
	ds_read_b128 v[144:147], v168
	ds_read_b128 v[148:151], v168 offset:1024
	ds_read_b128 v[164:167], v168 offset:2048
	ds_read_b128 v[168:171], v168 offset:3072
	s_add_u32 s56, s56, 0x40000
	s_addc_u32 s57, s57, 0
	s_mov_b32 m0, s61
	v_lshl_add_u64 v[228:229], s[56:57], 0, v[156:157]
	ds_read_b128 v[172:175], v187 offset:32768
	ds_read_b128 v[176:179], v187 offset:33792
	ds_read_b128 v[188:191], v187 offset:34816
	ds_read_b128 v[202:205], v187 offset:35840
	ds_read_b128 v[206:209], v187 offset:36864
	ds_read_b128 v[210:213], v187 offset:37888
	ds_read_b128 v[214:217], v187 offset:38912
	ds_read_b128 v[218:221], v187 offset:39936
	global_load_lds_dwordx4 v[228:229], off
	v_lshl_add_u64 v[228:229], s[56:57], 0, v[154:155]
	s_mov_b32 m0, s82
	s_nop 0
	global_load_lds_dwordx4 v[228:229], off
	s_waitcnt vmcnt(8)
	s_waitcnt lgkmcnt(0)
	s_barrier
	s_setprio 1
	s_waitcnt lgkmcnt(0)
	v_mfma_f32_16x16x32_bf16 v[124:127], v[128:131], v[172:175], v[124:127]
	v_mfma_f32_16x16x32_bf16 v[120:123], v[136:139], v[172:175], v[120:123]
	v_mfma_f32_16x16x32_bf16 v[112:115], v[128:131], v[188:191], v[112:115]
	v_mfma_f32_16x16x32_bf16 v[104:107], v[136:139], v[188:191], v[104:107]
	v_mfma_f32_16x16x32_bf16 v[96:99], v[128:131], v[206:209], v[96:99]
	v_mfma_f32_16x16x32_bf16 v[88:91], v[136:139], v[206:209], v[88:91]
	v_mfma_f32_16x16x32_bf16 v[80:83], v[128:131], v[214:217], v[80:83]
	v_mfma_f32_16x16x32_bf16 v[72:75], v[136:139], v[214:217], v[72:75]
	v_mfma_f32_16x16x32_bf16 v[124:127], v[132:135], v[176:179], v[124:127]
	v_mfma_f32_16x16x32_bf16 v[120:123], v[140:143], v[176:179], v[120:123]
	v_mfma_f32_16x16x32_bf16 v[112:115], v[132:135], v[202:205], v[112:115]
	v_mfma_f32_16x16x32_bf16 v[104:107], v[140:143], v[202:205], v[104:107]
	v_mfma_f32_16x16x32_bf16 v[96:99], v[132:135], v[210:213], v[96:99]
	v_mfma_f32_16x16x32_bf16 v[88:91], v[140:143], v[210:213], v[88:91]
	v_mfma_f32_16x16x32_bf16 v[80:83], v[132:135], v[218:221], v[80:83]
	v_mfma_f32_16x16x32_bf16 v[72:75], v[140:143], v[218:221], v[72:75]
	s_setprio 0
	s_setprio 1
	s_setprio 0
	s_barrier
	s_add_i32 s56, s91, s54
	v_lshl_add_u64 v[184:185], v[184:185], 0, s[76:77]
	s_mov_b32 m0, s56
	ds_read_b128 v[172:175], v187 offset:49152
	ds_read_b128 v[176:179], v187 offset:50176
	ds_read_b128 v[188:191], v187 offset:51200
	ds_read_b128 v[202:205], v187 offset:52224
	ds_read_b128 v[206:209], v187 offset:53248
	ds_read_b128 v[210:213], v187 offset:54272
	ds_read_b128 v[214:217], v187 offset:55296
	ds_read_b128 v[218:221], v187 offset:56320
	global_load_lds_dwordx4 v[184:185], off
	s_add_i32 m0, s56, 0x2000
	s_add_u32 s38, s38, 0x40080
	v_lshl_add_u64 v[184:185], v[222:223], 0, s[76:77]
	s_addc_u32 s39, s39, 0
	s_add_i32 s56, s92, s54
	global_load_lds_dwordx4 v[184:185], off
	v_lshl_add_u64 v[184:185], s[38:39], 0, v[192:193]
	s_mov_b32 m0, s56
	s_nop 0
	global_load_lds_dwordx4 v[184:185], off
	v_lshl_add_u64 v[184:185], s[38:39], 0, v[152:153]
	s_add_i32 m0, s56, 0x2000
	s_nop 0
	global_load_lds_dwordx4 v[184:185], off
	v_lshl_add_u64 v[184:185], v[224:225], 0, s[76:77]
	s_mov_b32 m0, s68
	s_nop 0
	global_load_lds_dwordx4 v[184:185], off
	v_lshl_add_u64 v[184:185], v[226:227], 0, s[76:77]
	s_mov_b32 m0, s83
	s_nop 0
	global_load_lds_dwordx4 v[184:185], off
	s_waitcnt vmcnt(8)
	s_waitcnt lgkmcnt(0)
	s_barrier
	s_setprio 1
	s_waitcnt lgkmcnt(0)
	v_mfma_f32_16x16x32_bf16 v[60:63], v[128:131], v[172:175], v[60:63]
	v_mfma_f32_16x16x32_bf16 v[56:59], v[136:139], v[172:175], v[56:59]
	v_mfma_f32_16x16x32_bf16 v[48:51], v[128:131], v[188:191], v[48:51]
	v_mfma_f32_16x16x32_bf16 v[40:43], v[136:139], v[188:191], v[40:43]
	v_mfma_f32_16x16x32_bf16 v[32:35], v[128:131], v[206:209], v[32:35]
	v_mfma_f32_16x16x32_bf16 v[24:27], v[136:139], v[206:209], v[24:27]
	v_mfma_f32_16x16x32_bf16 v[16:19], v[128:131], v[214:217], v[16:19]
	v_mfma_f32_16x16x32_bf16 v[8:11], v[136:139], v[214:217], v[8:11]
	v_mfma_f32_16x16x32_bf16 v[60:63], v[132:135], v[176:179], v[60:63]
	v_mfma_f32_16x16x32_bf16 v[56:59], v[140:143], v[176:179], v[56:59]
	v_mfma_f32_16x16x32_bf16 v[48:51], v[132:135], v[202:205], v[48:51]
	v_mfma_f32_16x16x32_bf16 v[40:43], v[140:143], v[202:205], v[40:43]
	v_mfma_f32_16x16x32_bf16 v[32:35], v[132:135], v[210:213], v[32:35]
	v_mfma_f32_16x16x32_bf16 v[24:27], v[140:143], v[210:213], v[24:27]
	v_mfma_f32_16x16x32_bf16 v[16:19], v[132:135], v[218:221], v[16:19]
	v_mfma_f32_16x16x32_bf16 v[8:11], v[140:143], v[218:221], v[8:11]
	s_setprio 0
	s_setprio 1
	s_setprio 0
	s_barrier
	s_add_i32 s90, s90, 2
	s_add_u32 s88, s88, 0x100
	s_addc_u32 s89, s89, 0
	s_add_u32 s8, s8, 0x100
	s_addc_u32 s9, s9, 0
	s_cmp_gt_u32 s90, 13
	s_cbranch_scc0 .Lz258
	s_branch .LBB0_261

.LBB0_255:
	s_cmp_eq_u32 s86, 14
	s_cbranch_scc1 .Lz255
	s_add_u32 s88, s8, 0x100
	s_addc_u32 s89, s9, 0
	s_add_u32 s8, s38, 0x40080
	s_addc_u32 s9, s39, 0
	s_mov_b32 s90, -2
	s_add_u32 s38, s8, 0xfffc0080
	s_addc_u32 s39, s9, -1
	s_add_i32 s91, 0, 0x10000
	s_cmp_eq_u32 s90, 12
	s_cselect_b32 s57, s31, s39
	s_cselect_b32 s56, s47, s38
	s_cselect_b32 s39, s29, s89
	s_cselect_b32 s38, s87, s88
	s_add_i32 s94, 0, 0x14000
	v_add_u32_e32 v140, s91, v183
	v_add_u32_e32 v168, s94, v183
	ds_read_b128 v[128:131], v140
	ds_read_b128 v[132:135], v140 offset:1024
	ds_read_b128 v[136:139], v140 offset:2048
	ds_read_b128 v[140:143], v140 offset:3072
	ds_read_b128 v[144:147], v168
	ds_read_b128 v[148:151], v168 offset:1024
	ds_read_b128 v[164:167], v168 offset:2048
	ds_read_b128 v[168:171], v168 offset:3072
	v_lshl_add_u64 v[184:185], s[8:9], 0, v[162:163]
	s_add_i32 m0, s55, 0xc000
	ds_read_b128 v[172:175], v187
	ds_read_b128 v[176:179], v187 offset:1024
	ds_read_b128 v[188:191], v187 offset:2048
	ds_read_b128 v[202:205], v187 offset:3072
	ds_read_b128 v[206:209], v187 offset:4096
	ds_read_b128 v[210:213], v187 offset:5120
	ds_read_b128 v[214:217], v187 offset:6144
	ds_read_b128 v[218:221], v187 offset:7168
	global_load_lds_dwordx4 v[184:185], off
	v_lshl_add_u64 v[184:185], s[8:9], 0, v[160:161]
	s_add_i32 m0, s55, 0xe000
	s_nop 0
	global_load_lds_dwordx4 v[184:185], off
	s_add_i32 s85, s85, 1
	s_mul_i32 s6, s85, s43
	s_mul_hi_u32 s7, s85, s42
	s_add_i32 s7, s7, s6
	s_mul_i32 s6, s85, s42
	s_add_u32 s34, s6, s2
	s_addc_u32 s35, s7, s41
	v_mov_b64_e32 v[0:1], 0xf00
	v_cmp_lt_i64_e64 s[6:7], s[34:35], v[0:1]
	v_mov_b64_e32 v[0:1], 0xeff
	v_cmp_gt_i64_e32 vcc, s[34:35], v[0:1]
	s_cbranch_vccnz .LBB0_257
	s_ashr_i32 s28, s34, 31
	s_lshr_b32 s28, s28, 29
	s_add_i32 s28, s34, s28
	s_ashr_i32 s29, s28, 3
	s_and_b32 s28, s28, -8
	s_sub_i32 s28, s34, s28
	s_cmp_lt_i32 s28, 0
	s_movk_i32 s30, 0x1e1
	s_cselect_b32 s30, s30, 0x1e0
	s_mul_i32 s28, s28, s30
	s_add_i32 s28, s28, s29
	s_mul_hi_i32 s29, s28, 0x88888889
	s_add_i32 s29, s29, s28
	s_lshr_b32 s30, s29, 31
	s_ashr_i32 s29, s29, 6
	s_add_i32 s29, s29, s30
	s_lshl_b32 s30, s29, 3
	s_sub_i32 s31, 0x100, s30
	s_min_i32 s31, s31, 8
	s_abs_i32 s34, s31
	v_cvt_f32_u32_e32 v0, s34
	s_sub_i32 s36, 0, s34
	s_mulk_i32 s29, 0x78
	s_sub_i32 s29, s28, s29
	v_rcp_iflag_f32_e32 v0, v0
	s_abs_i32 s28, s29
	s_xor_b32 s35, s29, s31
	s_ashr_i32 s35, s35, 31
	v_mul_f32_e32 v0, 0x4f7ffffe, v0
	v_cvt_u32_f32_e32 v0, v0
	s_nop 0
	v_readfirstlane_b32 s37, v0
	s_mul_i32 s36, s36, s37
	s_mul_hi_u32 s36, s37, s36
	s_add_i32 s37, s37, s36
	s_mul_hi_u32 s36, s28, s37
	s_mul_i32 s37, s36, s34
	s_sub_i32 s28, s28, s37
	s_add_i32 s47, s36, 1
	s_sub_i32 s37, s28, s34
	s_cmp_ge_u32 s28, s34
	s_cselect_b32 s36, s47, s36
	s_cselect_b32 s28, s37, s28
	s_add_i32 s37, s36, 1
	s_cmp_ge_u32 s28, s34
	s_cselect_b32 s28, s37, s36
	s_xor_b32 s28, s28, s35
	s_sub_i32 s28, s28, s35
	s_mul_i32 s31, s28, s31
	s_sub_i32 s29, s29, s31
	s_add_i32 s30, s30, s29
